# barrier release now two-level: XCD leader polls the global replicated counter, then publishes a plain-store XCD-local flag that the other 31 WGs poll (L2-served)
# baseline (speedup 1.0000x reference)
; __device__ __forceinline__ unsigned xb_ld(unsigned* p)              { return __hip_atomic_load(p, __ATOMIC_RELAXED, __HIP_MEMORY_SCOPE_AGENT); }
; __device__ __forceinline__ unsigned xb_add(unsigned* p, unsigned v) { return __hip_atomic_fetch_add(p, v, __ATOMIC_RELAXED, __HIP_MEMORY_SCOPE_AGENT); }
; #define XB_SPIN(cond, bar) do { unsigned _sp = 0; while (cond) { __builtin_amdgcn_s_sleep(1); \
;     if ((++_sp & 255u) == 0u) { if (xb_ld(&(bar)[XB_TMO])) break; if (_sp > XB_SPIN_CAP) { atomicAdd(&(bar)[XB_TMO], 1u); break; } } } } while (0)
; __device__ __forceinline__ void xcd_barrier(const XcdBarrier& b) {
;     asm volatile("s_waitcnt vmcnt(0)" ::: "memory");
;     __syncthreads();
;     if (threadIdx.x == 0) {
;         unsigned* bar = b.bar;
;         __builtin_amdgcn_s_waitcnt(0);
;         unsigned nloc = b.st[0], nx = b.st[1];
;         if (nloc == 0u) { xcd_barrier_complete(bar, b.x, nloc, nx); b.st[0] = nloc; b.st[1] = nx; }
;         const unsigned old = xb_add(&bar[XB_XSUB(b.x)], 1u);
;         const unsigned gen = old / nloc;
;         if (old + 1u == (gen + 1u) * nloc) {
;             __builtin_amdgcn_fence(__ATOMIC_RELEASE, "agent");
;             asm volatile("s_waitcnt vmcnt(0)" ::: "memory");
;             const unsigned og = xb_add(&bar[XB_TOP], 1u);
;             const unsigned tg = og / nx;
;             if (og + 1u == (tg + 1u) * nx) xb_add(&bar[XB_TOPGEN], 1u);
;             else XB_SPIN(xb_ld(&bar[XB_TOPGEN]) == tg, bar);
;             __builtin_amdgcn_fence(__ATOMIC_ACQUIRE, "agent");
;             xb_add(&bar[XB_XGEN(b.x)], 1u);
;             asm volatile("s_waitcnt vmcnt(0)" ::: "memory");
;         } else {
;             XB_SPIN(xb_ld(&bar[XB_XGEN(b.x)]) == gen, bar);
;             __builtin_amdgcn_fence(__ATOMIC_ACQUIRE, "agent");
;             asm volatile("s_waitcnt vmcnt(0)" ::: "memory");
;         }
;     }
;     __syncthreads();
; }
.Lnb_loop_1:
	s_sleep 1
	v_mov_b32_e32 v9, 0x2404
	global_load_dword v8, v9, s[12:13] sc1
	s_add_u32 s8, s8, 1
	s_cmp_gt_u32 s8, 0x100000
	s_cbranch_scc1 .Lnb_done_1
	s_waitcnt vmcnt(0)
	v_cmp_lt_u32_e32 vcc, v8, v7
	s_cbranch_vccnz .Lnb_loop_1
	v_mov_b32_e32 v9, 0x2480
	global_store_dword v9, v1, s[12:13]
	s_branch .Lnb_done_1
.Lnb_lpoll_1:
	s_sleep 1
	v_mov_b32_e32 v9, 0x2480
	global_load_dword v8, v9, s[12:13] sc1
	s_add_u32 s8, s8, 1
	s_cmp_gt_u32 s8, 0x100000
	s_cbranch_scc1 .Lnb_done_1
	s_waitcnt vmcnt(0)
	v_cmp_lt_u32_e32 vcc, v8, v1
	s_cbranch_vccnz .Lnb_lpoll_1
